# grid barrier (layer-loop sites): follower blocks poll the global generation word directly; the per-XCD generation bump is dropped
# speedup vs baseline: 1.0473x; 1.0016x over previous
; __device__ __forceinline__ void xcd_barrier_complete(unsigned* bar, unsigned x, unsigned& nloc, unsigned& nx) {
;   const unsigned G = gridDim.x * gridDim.y * gridDim.z;
;   unsigned sum, cnt, mine, sp = 0u;
;   for (;;) {
;     sum = 0u; cnt = 0u; mine = 0u;
; #pragma unroll
;     for (unsigned j = 0; j < 16; ++j) { const unsigned c = xb_ld(&bar[XB_XCNT(j)]); sum += c; cnt += (c > 0u) ? 1u : 0u; mine = (j == x) ? c : mine; }
;     if (sum == G) break;
;     __builtin_amdgcn_s_sleep(1);
;     if ((++sp & 255u) == 0u) { if (xb_ld(&bar[XB_TMO])) break; if (sp > XB_SPIN_CAP) { atomicAdd(&bar[XB_TMO], 1u); break; } }
;   }
;   nloc = mine > 0u ? mine : 1u; nx = cnt > 0u ? cnt : 1u;
; }
; __device__ __forceinline__ void xcd_barrier(const XcdBarrier& b) {
;   asm volatile("s_waitcnt vmcnt(0)" ::: "memory");
;   __syncthreads();
;   if (threadIdx.x == 0) {
;     unsigned* bar = b.bar;
;     __builtin_amdgcn_s_waitcnt(0);
;     unsigned nloc = b.st[0], nx = b.st[1];
;     if (nloc == 0u) { xcd_barrier_complete(bar, b.x, nloc, nx); b.st[0] = nloc; b.st[1] = nx; }
;     const unsigned old = xb_add(&bar[XB_XSUB(b.x)], 1u);
;     const unsigned gen = old / nloc;
;     if (old + 1u == (gen + 1u) * nloc) {
;       __builtin_amdgcn_fence(__ATOMIC_RELEASE, "agent");
;       asm volatile("s_waitcnt vmcnt(0)" ::: "memory");
;       const unsigned og = xb_add(&bar[XB_TOP], 1u);
;       const unsigned tg = og / nx;
;       if (og + 1u == (tg + 1u) * nx) xb_add(&bar[XB_TOPGEN], 1u);
;       else XB_SPIN(xb_ld(&bar[XB_TOPGEN]) == tg, bar);
;       __builtin_amdgcn_fence(__ATOMIC_ACQUIRE, "agent");
;       xb_add(&bar[XB_XGEN(b.x)], 1u);
;       asm volatile("s_waitcnt vmcnt(0)" ::: "memory");
;     } else {
;       XB_SPIN(xb_ld(&bar[XB_XGEN(b.x)]) == gen, bar);
;       __builtin_amdgcn_fence(__ATOMIC_ACQUIRE, "agent");
;       asm volatile("s_waitcnt vmcnt(0)" ::: "memory");
;     }
;   }
;   __syncthreads();
; __global__ void __launch_bounds__(256, 2) fwd_megakernel(Params p) {
;     ...
;   for (int l = 0; l < 2; ++l) {
;     for (int rep = 0; rep < NREP(1); ++rep) {
;       for (int t = bid; t < 66 * 20; t += nb) inproj_tile(p, smem, l, t / 20, t % 20);
;       GSYNC();
;     }
;     for (int rep = 0; rep < NREP(2); ++rep) {
;       int* cntG = (int*)(ws + OFF_CNT) + l + 2 * rep;
;       int* cntH = (int*)(ws + OFF_CNT) + 8 + l + 2 * rep;
.LBB0_287:
	s_or_b64 exec, exec, s[2:3]
	v_readlane_b32 s0, v239, 1
	v_readlane_b32 s2, v239, 0
	v_readlane_b32 s1, v239, 2
	s_cmpk_lt_i32 s2, 0x528
	s_mul_i32 s0, s1, s0
	s_cselect_b64 s[4:5], -1, 0
	v_writelane_b32 v238, s4, 39
	s_mul_i32 s90, s0, s33
	s_add_u32 s0, s36, 0x1b2d2300
	v_writelane_b32 v238, s5, 40
	s_addc_u32 s1, s37, 0
	v_writelane_b32 v238, s0, 41
	s_mov_b32 s3, 0
	s_movk_i32 s40, 0x1e0
	v_writelane_b32 v238, s1, 42
	s_add_u32 s0, s36, 0x1b2d2500
	s_addc_u32 s1, s37, 0
	v_writelane_b32 v238, s0, 9
	v_mov_b32_e32 v2, 0x4000
	s_movk_i32 s91, 0x4000
	v_writelane_b32 v238, s1, 10
	s_add_u32 s0, s36, 0x1b2d2600
	s_addc_u32 s1, s37, 0
	v_writelane_b32 v238, s0, 11
	v_lshlrev_b32_e32 v196, 2, v172
	s_movk_i32 s33, 0x7fff
	v_writelane_b32 v238, s1, 12
	s_add_u32 s0, s36, 0x1b2d2700
	s_addc_u32 s1, s37, 0
	v_writelane_b32 v238, s0, 13
	s_movk_i32 s54, 0x50
	v_mov_b32_e32 v197, 0x358637bd
	v_writelane_b32 v238, s1, 14
	s_add_u32 s0, s36, 0x1b2d2800
	s_addc_u32 s1, s37, 0
	v_writelane_b32 v238, s0, 1
	s_mov_b32 s92, 0x800000
	v_mov_b32_e32 v198, 1
	v_writelane_b32 v238, s1, 2
	s_add_u32 s0, s36, 0x1b2d2900
	s_addc_u32 s1, s37, 0
	v_writelane_b32 v238, s0, 3
	s_movk_i32 s55, 0x200
	v_mov_b32_e32 v199, 0x2000
	v_writelane_b32 v238, s1, 4
	s_add_u32 s0, s36, 0x1b2d2a00
	s_addc_u32 s1, s37, 0
	v_writelane_b32 v238, s0, 5
	v_mov_b32_e32 v200, 0x1000
	s_movk_i32 s93, 0xffc0
	v_writelane_b32 v238, s1, 6
	s_add_u32 s0, s36, 0x1b2d2b00
	s_addc_u32 s1, s37, 0
	v_writelane_b32 v238, s0, 7
	v_lshlrev_b32_e32 v178, 2, v172
	v_mov_b32_e32 v201, 0x500000
	v_writelane_b32 v238, s1, 8
	s_add_u32 s0, s36, 0x1b2d2c00
	s_addc_u32 s1, s37, 0
	v_writelane_b32 v238, s0, 15
	v_mov_b32_e32 v202, 0x3e000000
	v_mov_b32_e32 v203, 0x7c
	v_writelane_b32 v238, s1, 16
	s_add_u32 s0, s36, 0x1b2d2d00
	s_addc_u32 s1, s37, 0
	v_writelane_b32 v238, s0, 17
	v_mov_b32_e32 v204, 0x9000
	v_mov_b32_e32 v205, 0x70
	v_writelane_b32 v238, s1, 18
	s_add_u32 s0, s36, 0x1b2d2e00
	s_addc_u32 s1, s37, 0
	v_writelane_b32 v239, s0, 55
	v_mov_b32_e32 v206, 0x3fff
	v_mov_b32_e32 v207, 0x8400
	v_writelane_b32 v239, s1, 56
	s_add_u32 s0, s36, 0x1b2d2f00
	s_addc_u32 s1, s37, 0
	v_writelane_b32 v239, s0, 3
	v_mov_b32_e32 v208, 0x7f800000
	v_mov_b32_e32 v209, 2
	v_writelane_b32 v239, s1, 4
	s_add_u32 s0, s36, 0x1b2d3000
	s_addc_u32 s1, s37, 0
	v_writelane_b32 v238, s0, 19
	v_readlane_b32 s4, v239, 39
	v_readlane_b32 s12, v239, 47
	v_writelane_b32 v238, s1, 20
	s_add_u32 s0, s36, 0x1b2d3100
	s_addc_u32 s1, s37, 0
	v_writelane_b32 v238, s0, 21
	v_readlane_b32 s13, v239, 48
	v_readlane_b32 s14, v239, 49
	v_writelane_b32 v238, s1, 22
	s_add_u32 s0, s36, 0x1b2d3200
	s_addc_u32 s1, s37, 0
	v_writelane_b32 v238, s0, 23
	v_readlane_b32 s15, v239, 50
	v_readlane_b32 s16, v239, 51
	v_writelane_b32 v238, s1, 24
	s_add_u32 s0, s36, 0x1b2d3300
	s_addc_u32 s1, s37, 0
	v_writelane_b32 v238, s0, 33
	v_readlane_b32 s17, v239, 52
	v_readlane_b32 s18, v239, 53
	v_writelane_b32 v238, s1, 34
	s_add_u32 s0, s36, 0x1b2d3400
	s_addc_u32 s1, s37, 0
	v_writelane_b32 v238, s0, 35
	s_cmp_eq_u32 s45, 15
	v_readlane_b32 s19, v239, 54
	v_writelane_b32 v238, s1, 36
	s_cselect_b64 s[0:1], -1, 0
	v_writelane_b32 v238, s0, 43
	s_cmp_eq_u32 s45, 14
	s_mov_b64 s[12:13], s[16:17]
	v_writelane_b32 v238, s1, 44
	s_cselect_b64 s[0:1], -1, 0
	v_writelane_b32 v238, s0, 45
	s_cmp_eq_u32 s45, 13
	v_bfrev_b32_e32 v210, 4
	v_writelane_b32 v238, s1, 46
	s_cselect_b64 s[0:1], -1, 0
	v_writelane_b32 v238, s0, 47
	s_cmp_eq_u32 s45, 12
	s_mov_b32 s24, s3
	v_writelane_b32 v238, s1, 48
	s_cselect_b64 s[0:1], -1, 0
	v_writelane_b32 v238, s0, 49
	s_cmp_eq_u32 s45, 11
	s_waitcnt lgkmcnt(0)
	v_writelane_b32 v238, s1, 50
	s_cselect_b64 s[0:1], -1, 0
	v_writelane_b32 v238, s0, 51
	s_cmp_eq_u32 s45, 10
	s_barrier
	v_writelane_b32 v238, s1, 52
	s_cselect_b64 s[0:1], -1, 0
	v_writelane_b32 v238, s0, 53
	s_cmp_eq_u32 s45, 9
	s_nop 0
	v_writelane_b32 v238, s1, 54
	s_cselect_b64 s[0:1], -1, 0
	v_writelane_b32 v238, s0, 55
	s_cmp_eq_u32 s45, 8
	v_readlane_b32 s5, v239, 40
	v_writelane_b32 v238, s1, 56
	s_cselect_b64 s[0:1], -1, 0
	v_writelane_b32 v238, s0, 57
	s_cmp_eq_u32 s45, 7
	v_readlane_b32 s6, v239, 41
	v_writelane_b32 v238, s1, 58
	s_cselect_b64 s[0:1], -1, 0
	v_writelane_b32 v238, s0, 59
	s_cmp_eq_u32 s45, 6
	v_readlane_b32 s7, v239, 42
	v_writelane_b32 v238, s1, 60
	s_cselect_b64 s[0:1], -1, 0
	v_writelane_b32 v238, s0, 61
	s_cmp_eq_u32 s45, 5
	v_readlane_b32 s8, v239, 43
	v_writelane_b32 v238, s1, 62
	s_cselect_b64 s[0:1], -1, 0
	v_writelane_b32 v238, s0, 63
	s_cmp_eq_u32 s45, 4
	v_readlane_b32 s9, v239, 44
	v_writelane_b32 v237, s1, 0
	s_cselect_b64 s[0:1], -1, 0
	v_writelane_b32 v237, s0, 1
	s_cmp_eq_u32 s45, 3
	v_readlane_b32 s10, v239, 45
	v_writelane_b32 v237, s1, 2
	s_cselect_b64 s[0:1], -1, 0
	v_writelane_b32 v237, s0, 3
	s_cmp_eq_u32 s45, 2
	v_readlane_b32 s11, v239, 46
	v_writelane_b32 v237, s1, 4
	s_cselect_b64 s[0:1], -1, 0
	v_writelane_b32 v237, s0, 5
	s_cmp_eq_u32 s45, 1
	s_mov_b64 s[14:15], s[18:19]
	v_writelane_b32 v237, s1, 6
	s_cselect_b64 s[0:1], -1, 0
	v_writelane_b32 v237, s0, 7
	s_cmp_eq_u32 s45, 0
	s_nop 0
	v_writelane_b32 v237, s1, 8
	s_cselect_b64 s[0:1], -1, 0
	v_writelane_b32 v237, s0, 9
	s_nop 1
	v_writelane_b32 v237, s1, 10
	v_readlane_b32 s0, v239, 5
	v_readlane_b32 s1, v239, 6
	s_nop 1
	v_lshl_add_u64 v[0:1], v[0:1], 2, s[0:1]
	s_mov_b64 s[0:1], 0x1400
	v_lshl_add_u64 v[174:175], v[0:1], 0, s[0:1]
	s_mov_b64 s[0:1], 0x2400
	v_lshl_add_u64 v[176:177], v[0:1], 0, s[0:1]
	s_add_u32 s0, s36, 0x1b2d5500
	s_addc_u32 s1, s37, 0
	v_writelane_b32 v237, s0, 11
	v_lshrrev_b32_e32 v0, 5, v172
	v_mov_b32_e32 v1, 0
	v_writelane_b32 v237, s1, 12
	s_add_u32 s0, s36, 0x1b2d5600
	s_addc_u32 s1, s37, 0
	v_mov_b64_e32 v[176:177], s[0:1]
	v_writelane_b32 v237, s0, 13
	v_mad_u32_u24 v194, v0, s40, v172
	v_lshl_or_b32 v195, v0, 8, v2
	v_writelane_b32 v237, s1, 14
	s_add_u32 s0, s36, 0x1b2ca000
	v_writelane_b32 v237, s0, 15
	s_addc_u32 s0, s37, 0
	v_writelane_b32 v237, s0, 16
	s_add_u32 s0, s36, 0x1b2ca020
	v_writelane_b32 v237, s0, 17
	s_addc_u32 s0, s37, 0
	v_writelane_b32 v237, s0, 18
	v_cmp_eq_u32_e64 s[0:1], 0, v148
	s_nop 1
	v_writelane_b32 v237, s0, 19
	s_nop 1
	v_writelane_b32 v237, s1, 20
	s_add_u32 s0, s36, 0x1b2ca100
	v_writelane_b32 v237, s0, 21
	s_addc_u32 s0, s37, 0
	v_writelane_b32 v237, s0, 22
	s_add_u32 s0, s36, 0x1b2ca040
	s_addc_u32 s1, s37, 0
	v_writelane_b32 v237, s0, 23
	s_cmpk_lt_i32 s2, 0x108
	s_nop 0
	v_writelane_b32 v237, s1, 24
	s_cselect_b64 s[0:1], -1, 0
	v_writelane_b32 v237, s0, 25
	s_nop 1
	v_writelane_b32 v237, s1, 26
	s_add_u32 s0, s12, 0x100
	s_addc_u32 s1, s13, 0
	v_writelane_b32 v237, s0, 27
	s_nop 1
	v_writelane_b32 v237, s1, 28
	s_mov_b64 s[0:1], -1
	v_writelane_b32 v237, s0, 29
	s_nop 1
	v_writelane_b32 v237, s1, 30
	v_writelane_b32 v237, s90, 31
	s_branch .LBB0_291
.LBB0_288:
	s_or_b64 exec, exec, s[4:5]
	s_waitcnt vmcnt(0) lgkmcnt(0)
	buffer_inv sc1
	s_waitcnt vmcnt(0)
.LBB0_289:
	s_or_b64 exec, exec, s[0:1]
	s_mov_b64 s[0:1], 0
	s_waitcnt lgkmcnt(0)
	s_barrier

; __device__ __forceinline__ unsigned xcc_id() { return (unsigned)__builtin_amdgcn_s_getreg(20 | (3 << 11)) & 0xfu; }
; __device__ __forceinline__ unsigned cu_key() { return ((unsigned)__builtin_amdgcn_s_getreg(63492) >> 8) & 0xffu; }
; __device__ __forceinline__ unsigned xb_ld(unsigned* p) { return __hip_atomic_load(p, __ATOMIC_RELAXED, __HIP_MEMORY_SCOPE_AGENT); }
; __device__ __forceinline__ unsigned xb_add(unsigned* p, unsigned v) { return __hip_atomic_fetch_add(p, v, __ATOMIC_RELAXED, __HIP_MEMORY_SCOPE_AGENT); }
; #define XB_SPIN(cond, bar) do { unsigned _sp = 0; while (cond) { __builtin_amdgcn_s_sleep(1); \
;     if ((++_sp & 255u) == 0u) { if (xb_ld(&(bar)[XB_TMO])) break; if (_sp > XB_SPIN_CAP) { atomicAdd(&(bar)[XB_TMO], 1u); break; } } } } while (0)
; __device__ __forceinline__ void xcd_barrier(const XcdBarrier& b) {
;     ...
;       __builtin_amdgcn_fence(__ATOMIC_RELEASE, "agent");
;       asm volatile("s_waitcnt vmcnt(0)" ::: "memory");
;       const unsigned og = xb_add(&bar[XB_TOP], 1u);
;       const unsigned tg = og / nx;
;       if (og + 1u == (tg + 1u) * nx) xb_add(&bar[XB_TOPGEN], 1u);
;       else XB_SPIN(xb_ld(&bar[XB_TOPGEN]) == tg, bar);
;       __builtin_amdgcn_fence(__ATOMIC_ACQUIRE, "agent");
;       xb_add(&bar[XB_XGEN(b.x)], 1u);
;       asm volatile("s_waitcnt vmcnt(0)" ::: "memory");
;     } else {
;       XB_SPIN(xb_ld(&bar[XB_XGEN(b.x)]) == gen, bar);
;       __builtin_amdgcn_fence(__ATOMIC_ACQUIRE, "agent");
;       asm volatile("s_waitcnt vmcnt(0)" ::: "memory");
;     }
;   }
;   __syncthreads();
; __global__ void __launch_bounds__(256, 2) fwd_megakernel(Params p) {
;     ...
;       if (tid == 0) {
;         unsigned key = xcc_id() * 256 + cu_key();
;         stage = (atomicAdd(&claim[key], 1) == 0) ? 0 : 1;
;       }
.LBB0_672:
	s_or_b64 exec, exec, s[4:5]
	s_and_saveexec_b64 s[4:5], s[6:7]
	s_cbranch_execz .LBB0_674
	global_atomic_add v[2:3], v198, off
.LBB0_674:
	s_or_b64 exec, exec, s[4:5]
	s_waitcnt vmcnt(0) lgkmcnt(0)
	buffer_inv sc1
	s_waitcnt vmcnt(0)
.LBB0_675:
	s_or_b64 exec, exec, s[0:1]
	v_mov_b32_e32 v152, 1
	s_waitcnt lgkmcnt(0)
	s_barrier
	s_mov_b64 s[0:1], exec
	v_readlane_b32 s4, v237, 19
	v_readlane_b32 s5, v237, 20
	s_and_b64 s[4:5], s[0:1], s[4:5]
	s_mov_b64 exec, s[4:5]
	s_cbranch_execz .LBB0_677
	s_lshl_b32 s2, s24, 11
	s_lshl_b64 s[4:5], s[2:3], 2
	v_readlane_b32 s2, v237, 21
	s_add_u32 s2, s2, s4
	v_readlane_b32 s4, v237, 22
	s_addc_u32 s5, s4, s5
	s_getreg_b32 s4, hwreg(HW_REG_XCC_ID, 0, 4)
	s_lshl_b32 s4, s4, 8
	s_getreg_b32 s6, hwreg(HW_REG_HW_ID)
	s_and_b32 s4, s4, 0xf00
	s_bfe_u32 s6, s6, 0x80008
	s_or_b32 s4, s6, s4
	s_lshl_b32 s4, s4, 2
	s_add_u32 s4, s2, s4
	s_addc_u32 s5, s5, 0
	v_mov_b64_e32 v[2:3], s[4:5]
	global_atomic_add v0, v[2:3], v198, off sc0
	s_waitcnt vmcnt(0) lgkmcnt(0)
	v_cmp_ne_u32_e32 vcc, 0, v0
	s_nop 1
	v_cndmask_b32_e64 v152, 0, 1, vcc

; #define GSYNC() do { xcd_barrier(xb); if (REP_MASK & 256) xcd_barrier(xb); } while (0)
; __device__ __forceinline__ unsigned xb_ld(unsigned* p) { return __hip_atomic_load(p, __ATOMIC_RELAXED, __HIP_MEMORY_SCOPE_AGENT); }
; __device__ __forceinline__ unsigned xb_add(unsigned* p, unsigned v) { return __hip_atomic_fetch_add(p, v, __ATOMIC_RELAXED, __HIP_MEMORY_SCOPE_AGENT); }
; #define XB_SPIN(cond, bar) do { unsigned _sp = 0; while (cond) { __builtin_amdgcn_s_sleep(1); \
;     if ((++_sp & 255u) == 0u) { if (xb_ld(&(bar)[XB_TMO])) break; if (_sp > XB_SPIN_CAP) { atomicAdd(&(bar)[XB_TMO], 1u); break; } } } } while (0)
; __device__ __forceinline__ void xcd_barrier(const XcdBarrier& b) {
;     ...
;       __builtin_amdgcn_fence(__ATOMIC_RELEASE, "agent");
;       asm volatile("s_waitcnt vmcnt(0)" ::: "memory");
;       const unsigned og = xb_add(&bar[XB_TOP], 1u);
;       const unsigned tg = og / nx;
;       if (og + 1u == (tg + 1u) * nx) xb_add(&bar[XB_TOPGEN], 1u);
;       else XB_SPIN(xb_ld(&bar[XB_TOPGEN]) == tg, bar);
;       __builtin_amdgcn_fence(__ATOMIC_ACQUIRE, "agent");
;       xb_add(&bar[XB_XGEN(b.x)], 1u);
;       asm volatile("s_waitcnt vmcnt(0)" ::: "memory");
;     } else {
;       XB_SPIN(xb_ld(&bar[XB_XGEN(b.x)]) == gen, bar);
;       __builtin_amdgcn_fence(__ATOMIC_ACQUIRE, "agent");
;       asm volatile("s_waitcnt vmcnt(0)" ::: "memory");
;     }
;   }
;   __syncthreads();
; __global__ void __launch_bounds__(256, 2) fwd_megakernel(Params p) {
;     ...
;       GSYNC();
;     }
;     for (int rep = 0; rep < NREP(3); ++rep) {
;       const int ntl = 512 + (l == 0 ? 64 : 0);
;       for (int t = bid; t < ntl; t += nb) {
.LBB0_1189:
	s_or_b64 exec, exec, s[4:5]
	s_and_saveexec_b64 s[4:5], s[6:7]
	s_cbranch_execz .LBB0_1191
	global_atomic_add v[2:3], v198, off
.LBB0_1191:
	s_or_b64 exec, exec, s[4:5]
	s_waitcnt vmcnt(0) lgkmcnt(0)
	buffer_inv sc1
	s_waitcnt vmcnt(0)
.LBB0_1192:
	s_or_b64 exec, exec, s[0:1]
	v_readlane_b32 s0, v237, 29
	v_readlane_b32 s1, v237, 30
	s_and_b64 s[0:1], s[0:1], exec
	s_movk_i32 s0, 0x240
	s_cselect_b32 s16, s0, 0x200
	v_readlane_b32 s17, v239, 0
	s_waitcnt lgkmcnt(0)
	s_barrier
	s_branch .LBB0_1195

; #define LAUNDER(v) asm volatile("" : "+s"(v))
; __device__ __forceinline__ unsigned xb_ld(unsigned* p) { return __hip_atomic_load(p, __ATOMIC_RELAXED, __HIP_MEMORY_SCOPE_AGENT); }
; __device__ __forceinline__ unsigned xb_add(unsigned* p, unsigned v) { return __hip_atomic_fetch_add(p, v, __ATOMIC_RELAXED, __HIP_MEMORY_SCOPE_AGENT); }
; #define XB_SPIN(cond, bar) do { unsigned _sp = 0; while (cond) { __builtin_amdgcn_s_sleep(1); \
;     if ((++_sp & 255u) == 0u) { if (xb_ld(&(bar)[XB_TMO])) break; if (_sp > XB_SPIN_CAP) { atomicAdd(&(bar)[XB_TMO], 1u); break; } } } } while (0)
; __device__ __forceinline__ int vtid() { int t = threadIdx.x; asm volatile("" : "+v"(t)); return t; }
; __device__ __forceinline__ void xcd_barrier(const XcdBarrier& b) {
;     ...
;       __builtin_amdgcn_fence(__ATOMIC_RELEASE, "agent");
;       asm volatile("s_waitcnt vmcnt(0)" ::: "memory");
;       const unsigned og = xb_add(&bar[XB_TOP], 1u);
;       const unsigned tg = og / nx;
;       if (og + 1u == (tg + 1u) * nx) xb_add(&bar[XB_TOPGEN], 1u);
;       else XB_SPIN(xb_ld(&bar[XB_TOPGEN]) == tg, bar);
;       __builtin_amdgcn_fence(__ATOMIC_ACQUIRE, "agent");
;       xb_add(&bar[XB_XGEN(b.x)], 1u);
;       asm volatile("s_waitcnt vmcnt(0)" ::: "memory");
;     } else {
;       XB_SPIN(xb_ld(&bar[XB_XGEN(b.x)]) == gen, bar);
;       __builtin_amdgcn_fence(__ATOMIC_ACQUIRE, "agent");
;       asm volatile("s_waitcnt vmcnt(0)" ::: "memory");
;     }
;   }
;   __syncthreads();
; __device__ __forceinline__ void router_rows(const Params& p, char* smem, int l, int nrows) {
;   const int tid = vtid(), lane = tid & 63, wid = tid >> 6;
;   char* ws = p.ws;
;   LAUNDER(ws); LAUNDER(l);
;   const float* XR = l == 0 ? (const float*)(ws + OFF_XNEW) : p.out;
;   u16* H2 = (u16*)(ws + OFF_H2);
;   const float* nw = p.norm2_w + l * 1024;
;   const float* wr = p.w_router + (size_t)l * 1024 * 16;
;   float* Hs = (float*)smem;
;   float* red = Hs + 256 * 36;
;   const int ngroups = nrows >> 3;
;   for (int grp = blockIdx.x; grp < ngroups; grp += gridDim.x) {
;     __syncthreads();
; #pragma unroll
;     for (int rr = 0; rr < 2; ++rr) {
;       const int rl = wid * 2 + rr;
;       const int row = grp * 8 + rl;
;       const float* src = XR + (size_t)row * 1024;
;       int v = row < MLAT ? (row >> 13) : 2;
;       const float* mods = (const float*)(ws + OFF_MODS) + (l * 3 + v) * 6144;
.LBB0_1264:
	s_or_b64 exec, exec, s[4:5]
	s_and_saveexec_b64 s[4:5], s[6:7]
	s_cbranch_execz .LBB0_1266
	global_atomic_add v[2:3], v198, off
.LBB0_1266:
	s_or_b64 exec, exec, s[4:5]
	s_waitcnt vmcnt(0) lgkmcnt(0)
	buffer_inv sc1
	s_waitcnt vmcnt(0)
.LBB0_1267:
	s_or_b64 exec, exec, s[0:1]
	v_readlane_b32 s0, v237, 29
	v_readlane_b32 s1, v237, 30
	s_and_b64 s[0:1], s[0:1], exec
	s_movk_i32 s0, 0x840
	s_cselect_b32 s2, s0, 0x800
	v_readlane_b32 s0, v239, 0
	s_cmp_lt_i32 s0, s2
	v_mov_b32_e32 v2, v172
	s_mov_b64 s[4:5], s[58:59]
	v_readlane_b32 s0, v239, 63
	s_waitcnt lgkmcnt(0)
	s_barrier
	v_readlane_b32 s1, v238, 0
	s_cbranch_scc0 .LBB0_1279
	v_and_b32_e32 v0, 64, v173
	v_add_u32_e32 v0, 64, v0
	v_xor_b32_e32 v3, 32, v173
	v_cmp_lt_i32_e32 vcc, v3, v0
	s_add_u32 s1, s4, 0x2a196100
	s_addc_u32 s6, s5, 0
	v_cndmask_b32_e32 v3, v173, v3, vcc
	s_waitcnt vmcnt(0)
	v_lshlrev_b32_e32 v52, 2, v3
	v_xor_b32_e32 v3, 16, v173
	v_cmp_lt_i32_e32 vcc, v3, v0
	s_cmp_eq_u32 s0, 0
	v_readlane_b32 s12, v239, 7
	v_cndmask_b32_e32 v3, v173, v3, vcc
	v_lshlrev_b32_e32 v53, 2, v3
	v_xor_b32_e32 v3, 8, v173
	v_cmp_lt_i32_e32 vcc, v3, v0
	s_cselect_b32 s7, s6, s57
	s_cselect_b32 s6, s1, s56
	v_cndmask_b32_e32 v3, v173, v3, vcc
	v_lshlrev_b32_e32 v54, 2, v3
	v_xor_b32_e32 v3, 4, v173
	v_cmp_lt_i32_e32 vcc, v3, v0
	s_lshl_b32 s8, s0, 10
	v_readlane_b32 s13, v239, 8
	v_readlane_b32 s14, v239, 9
	v_readlane_b32 s15, v239, 10
	v_readlane_b32 s24, v239, 19
	v_readlane_b32 s25, v239, 20
	v_cndmask_b32_e32 v3, v173, v3, vcc
	s_ashr_i32 s9, s8, 31
	v_readlane_b32 s26, v239, 21
	v_readlane_b32 s27, v239, 22
	s_mov_b64 s[12:13], s[24:25]
	v_lshlrev_b32_e32 v55, 2, v3
	v_xor_b32_e32 v3, 2, v173
	s_lshl_b64 s[8:9], s[8:9], 2
	s_mov_b64 s[14:15], s[26:27]
	v_cmp_lt_i32_e32 vcc, v3, v0
	s_add_u32 s10, s14, s8
	v_readlane_b32 s16, v239, 11
	v_cndmask_b32_e32 v3, v173, v3, vcc
	v_readlane_b32 s17, v239, 12
	v_readlane_b32 s18, v239, 13
	v_readlane_b32 s19, v239, 14
	s_addc_u32 s11, s15, s9
	s_ashr_i32 s1, s0, 31
	v_lshlrev_b32_e32 v56, 2, v3
	v_xor_b32_e32 v3, 1, v173
	s_lshl_b64 s[8:9], s[0:1], 16
	v_readlane_b32 s12, v238, 25
	v_cmp_lt_i32_e32 vcc, v3, v0
	s_add_u32 s12, s12, s8
	s_mul_i32 s8, s0, 3
	v_cndmask_b32_e32 v0, v173, v3, vcc
	v_and_b32_e32 v3, -16, v2
	s_movk_i32 s0, 0x90
	v_lshlrev_b32_e32 v57, 2, v0
	v_ashrrev_i32_e32 v59, 4, v2
	v_mul_lo_u32 v0, v3, s0
	s_movk_i32 s0, 0x80
	v_and_b32_e32 v58, 15, v2
	v_lshlrev_b32_e32 v4, 6, v59
	v_cmp_gt_i32_e64 s[40:41], s0, v2
	s_movk_i32 s0, 0xff74
	v_and_b32_e32 v8, 63, v2
	v_readlane_b32 s13, v238, 26
	v_ashrrev_i32_e32 v10, 6, v2
	v_ashrrev_i32_e32 v5, 31, v4
	v_lshlrev_b32_e32 v6, 2, v58
	v_lshlrev_b32_e32 v60, 2, v2
	v_mad_u64_u32 v[2:3], s[0:1], v3, s0, v[0:1]
	s_addc_u32 s13, s13, s9
	v_lshlrev_b64 v[4:5], 6, v[4:5]
	v_or_b32_e32 v61, v2, v6
	v_lshlrev_b32_e32 v2, 15, v58
	v_mov_b32_e32 v3, v1
	v_lshl_add_u64 v[4:5], s[12:13], 0, v[4:5]
	v_lshl_add_u64 v[2:3], s[4:5], 0, v[2:3]
	s_mov_b64 s[12:13], 0x2e396100
	v_mov_b32_e32 v7, v1
	v_lshl_add_u64 v[16:17], v[2:3], 0, s[12:13]
	v_lshlrev_b32_e32 v2, 4, v8
	v_mov_b32_e32 v3, v1
	v_lshl_add_u64 v[14:15], v[4:5], 0, v[6:7]
	v_lshl_add_u64 v[18:19], s[10:11], 0, v[2:3]
	v_or_b32_e32 v5, 64, v8
	v_lshl_add_u64 v[20:21], s[6:7], 0, v[2:3]
	v_lshl_add_u64 v[2:3], s[4:5], 0, v[2:3]
	s_mov_b64 s[6:7], 0x18e00000
	v_lshlrev_b32_e32 v33, 1, v10
	s_add_u32 s0, s4, 0x2e496100
	v_mul_u32_u24_e32 v64, 0x90, v5
	v_or_b32_e32 v5, 0x80, v8
	v_lshl_add_u64 v[22:23], v[2:3], 0, s[6:7]
	v_lshlrev_b32_e32 v2, 3, v8
	v_mov_b32_e32 v3, v1
	v_lshlrev_b32_e32 v9, 2, v8
	v_lshlrev_b32_e32 v4, 9, v10
	s_addc_u32 s1, s5, 0
	v_mul_u32_u24_e32 v65, 0x90, v5
	v_or_b32_e32 v5, 0xc0, v8
	v_or_b32_e32 v67, 1, v33
	v_lshl_add_u64 v[2:3], s[4:5], 0, v[2:3]
	s_mov_b64 s[4:5], 0x1d3d6100
	v_cmp_gt_u32_e64 s[38:39], 16, v8
	v_lshlrev_b32_e32 v62, 5, v10
	v_mul_u32_u24_e32 v63, 0x90, v8
	v_mul_u32_u24_e32 v66, 0x90, v5
	v_lshlrev_b32_e32 v68, 4, v67
	v_lshl_add_u64 v[24:25], v[2:3], 0, s[4:5]
	v_add_u32_e32 v69, v9, v4
	v_readlane_b32 s9, v239, 0
	v_readlane_b32 s20, v239, 15
	v_readlane_b32 s21, v239, 16
	v_readlane_b32 s22, v239, 17
	v_readlane_b32 s23, v239, 18
	v_readlane_b32 s14, v238, 27
	v_readlane_b32 s15, v238, 28
	v_readlane_b32 s16, v238, 29
	v_readlane_b32 s17, v238, 30
	v_readlane_b32 s18, v238, 31
	v_readlane_b32 s19, v238, 32
	s_branch .LBB0_1270

; __device__ __forceinline__ unsigned xb_ld(unsigned* p) { return __hip_atomic_load(p, __ATOMIC_RELAXED, __HIP_MEMORY_SCOPE_AGENT); }
; __device__ __forceinline__ unsigned xb_add(unsigned* p, unsigned v) { return __hip_atomic_fetch_add(p, v, __ATOMIC_RELAXED, __HIP_MEMORY_SCOPE_AGENT); }
; #define XB_SPIN(cond, bar) do { unsigned _sp = 0; while (cond) { __builtin_amdgcn_s_sleep(1); \
;     if ((++_sp & 255u) == 0u) { if (xb_ld(&(bar)[XB_TMO])) break; if (_sp > XB_SPIN_CAP) { atomicAdd(&(bar)[XB_TMO], 1u); break; } } } } while (0)
; __device__ __forceinline__ void xcd_barrier(const XcdBarrier& b) {
;     ...
;       __builtin_amdgcn_fence(__ATOMIC_RELEASE, "agent");
;       asm volatile("s_waitcnt vmcnt(0)" ::: "memory");
;       const unsigned og = xb_add(&bar[XB_TOP], 1u);
;       const unsigned tg = og / nx;
;       if (og + 1u == (tg + 1u) * nx) xb_add(&bar[XB_TOPGEN], 1u);
;       else XB_SPIN(xb_ld(&bar[XB_TOPGEN]) == tg, bar);
;       __builtin_amdgcn_fence(__ATOMIC_ACQUIRE, "agent");
;       xb_add(&bar[XB_XGEN(b.x)], 1u);
;       asm volatile("s_waitcnt vmcnt(0)" ::: "memory");
;     } else {
;       XB_SPIN(xb_ld(&bar[XB_XGEN(b.x)]) == gen, bar);
;       __builtin_amdgcn_fence(__ATOMIC_ACQUIRE, "agent");
;       asm volatile("s_waitcnt vmcnt(0)" ::: "memory");
;     }
;   }
;   __syncthreads();
; __global__ void __launch_bounds__(256, 2) fwd_megakernel(Params p) {
;     ...
;     }
;     for (int rep = 0; rep < NREP(5); ++rep) {
;       const int nj = l == 0 ? 64 : 32;
;       for (int j = bid; j < nj; j += nb) topk_job(p, smem, j & 31, j >= 32);
.LBB0_1320:
	s_or_b64 exec, exec, s[4:5]
	s_and_saveexec_b64 s[4:5], s[6:7]
	s_cbranch_execz .LBB0_1322
	global_atomic_add v[2:3], v198, off
.LBB0_1322:
	s_or_b64 exec, exec, s[4:5]
	s_waitcnt vmcnt(0) lgkmcnt(0)
	buffer_inv sc1
	s_waitcnt vmcnt(0)
.LBB0_1323:
	s_or_b64 exec, exec, s[0:1]
	v_readlane_b32 s0, v237, 29
	v_readlane_b32 s1, v237, 30
	s_and_b64 s[0:1], s[0:1], exec
	s_cselect_b32 s0, 64, 32
	v_readlane_b32 s2, v239, 0
	s_cmp_ge_i32 s2, s0
	s_waitcnt lgkmcnt(0)
	s_barrier
	v_writelane_b32 v237, s0, 32
	s_cbranch_scc0 .LBB0_1329

; #define GSYNC() do { xcd_barrier(xb); if (REP_MASK & 256) xcd_barrier(xb); } while (0)
; __device__ __forceinline__ unsigned xb_ld(unsigned* p) { return __hip_atomic_load(p, __ATOMIC_RELAXED, __HIP_MEMORY_SCOPE_AGENT); }
; __device__ __forceinline__ unsigned xb_add(unsigned* p, unsigned v) { return __hip_atomic_fetch_add(p, v, __ATOMIC_RELAXED, __HIP_MEMORY_SCOPE_AGENT); }
; #define XB_SPIN(cond, bar) do { unsigned _sp = 0; while (cond) { __builtin_amdgcn_s_sleep(1); \
;     if ((++_sp & 255u) == 0u) { if (xb_ld(&(bar)[XB_TMO])) break; if (_sp > XB_SPIN_CAP) { atomicAdd(&(bar)[XB_TMO], 1u); break; } } } } while (0)
; __device__ __forceinline__ void xcd_barrier(const XcdBarrier& b) {
;     ...
;       __builtin_amdgcn_fence(__ATOMIC_RELEASE, "agent");
;       asm volatile("s_waitcnt vmcnt(0)" ::: "memory");
;       const unsigned og = xb_add(&bar[XB_TOP], 1u);
;       const unsigned tg = og / nx;
;       if (og + 1u == (tg + 1u) * nx) xb_add(&bar[XB_TOPGEN], 1u);
;       else XB_SPIN(xb_ld(&bar[XB_TOPGEN]) == tg, bar);
;       __builtin_amdgcn_fence(__ATOMIC_ACQUIRE, "agent");
;       xb_add(&bar[XB_XGEN(b.x)], 1u);
;       asm volatile("s_waitcnt vmcnt(0)" ::: "memory");
;     } else {
;       XB_SPIN(xb_ld(&bar[XB_XGEN(b.x)]) == gen, bar);
;       __builtin_amdgcn_fence(__ATOMIC_ACQUIRE, "agent");
;       asm volatile("s_waitcnt vmcnt(0)" ::: "memory");
;     }
;   }
;   __syncthreads();
; __global__ void __launch_bounds__(256, 2) fwd_megakernel(Params p) {
;     ...
;       GSYNC();
;     }
;     for (int rep = 0; rep < NREP(6); ++rep) {
;       const int nl = 4096, ncx = l == 0 ? 512 : 0;
;       for (int t = bid; t < nl + ncx; t += nb) {
.LBB0_1632:
	s_or_b64 exec, exec, s[4:5]
	s_and_saveexec_b64 s[4:5], s[6:7]
	s_cbranch_execz .LBB0_1634
	global_atomic_add v[2:3], v198, off
.LBB0_1634:
	s_or_b64 exec, exec, s[4:5]
	s_waitcnt vmcnt(0) lgkmcnt(0)
	buffer_inv sc1
	s_waitcnt vmcnt(0)
.LBB0_1635:
	s_or_b64 exec, exec, s[0:1]
	v_readlane_b32 s0, v237, 29
	v_readlane_b32 s1, v237, 30
	s_and_b64 s[0:1], s[0:1], exec
	s_movk_i32 s0, 0x1200
	s_cselect_b32 s2, s0, 0x1000
	v_readlane_b32 s12, v239, 0
	s_cmp_ge_i32 s12, s2
	s_movk_i32 s91, 0x4000
	s_waitcnt lgkmcnt(0)
	s_barrier
	s_cbranch_scc0 .LBB0_1640

; #define GSYNC() do { xcd_barrier(xb); if (REP_MASK & 256) xcd_barrier(xb); } while (0)
; __device__ __forceinline__ unsigned xb_ld(unsigned* p) { return __hip_atomic_load(p, __ATOMIC_RELAXED, __HIP_MEMORY_SCOPE_AGENT); }
; __device__ __forceinline__ unsigned xb_add(unsigned* p, unsigned v) { return __hip_atomic_fetch_add(p, v, __ATOMIC_RELAXED, __HIP_MEMORY_SCOPE_AGENT); }
; #define XB_SPIN(cond, bar) do { unsigned _sp = 0; while (cond) { __builtin_amdgcn_s_sleep(1); \
;     if ((++_sp & 255u) == 0u) { if (xb_ld(&(bar)[XB_TMO])) break; if (_sp > XB_SPIN_CAP) { atomicAdd(&(bar)[XB_TMO], 1u); break; } } } } while (0)
; __device__ __forceinline__ void xcd_barrier(const XcdBarrier& b) {
;     ...
;       __builtin_amdgcn_fence(__ATOMIC_RELEASE, "agent");
;       asm volatile("s_waitcnt vmcnt(0)" ::: "memory");
;       const unsigned og = xb_add(&bar[XB_TOP], 1u);
;       const unsigned tg = og / nx;
;       if (og + 1u == (tg + 1u) * nx) xb_add(&bar[XB_TOPGEN], 1u);
;       else XB_SPIN(xb_ld(&bar[XB_TOPGEN]) == tg, bar);
;       __builtin_amdgcn_fence(__ATOMIC_ACQUIRE, "agent");
;       xb_add(&bar[XB_XGEN(b.x)], 1u);
;       asm volatile("s_waitcnt vmcnt(0)" ::: "memory");
;     } else {
;       XB_SPIN(xb_ld(&bar[XB_XGEN(b.x)]) == gen, bar);
;       __builtin_amdgcn_fence(__ATOMIC_ACQUIRE, "agent");
;       asm volatile("s_waitcnt vmcnt(0)" ::: "memory");
;     }
;   }
;   __syncthreads();
; __global__ void __launch_bounds__(256, 2) fwd_megakernel(Params p) {
;     ...
;       GSYNC();
;     }
;     for (int rep = 0; rep < NREP(7); ++rep) {
;       const int nl = 1024, ncx = l == 0 ? 512 : 0;
;       for (int t = bid; t < nl + ncx; t += nb) {
.LBB0_1775:
	s_or_b64 exec, exec, s[4:5]
	s_and_saveexec_b64 s[4:5], s[6:7]
	s_cbranch_execz .LBB0_1777
	global_atomic_add v[2:3], v198, off
.LBB0_1777:
	s_or_b64 exec, exec, s[4:5]
	s_waitcnt vmcnt(0) lgkmcnt(0)
	buffer_inv sc1
	s_waitcnt vmcnt(0)
.LBB0_1778:
	s_or_b64 exec, exec, s[0:1]
	v_readlane_b32 s0, v237, 29
	v_readlane_b32 s1, v237, 30
	s_and_b64 s[0:1], s[0:1], exec
	s_movk_i32 s0, 0x600
	s_waitcnt lgkmcnt(0)
	s_barrier
	s_cselect_b32 s26, s0, 0x400
	v_readlane_b32 s27, v239, 0
	s_branch .LBB0_1780

; #define GSYNC() do { xcd_barrier(xb); if (REP_MASK & 256) xcd_barrier(xb); } while (0)
; __device__ __forceinline__ unsigned xb_ld(unsigned* p) { return __hip_atomic_load(p, __ATOMIC_RELAXED, __HIP_MEMORY_SCOPE_AGENT); }
; __device__ __forceinline__ unsigned xb_add(unsigned* p, unsigned v) { return __hip_atomic_fetch_add(p, v, __ATOMIC_RELAXED, __HIP_MEMORY_SCOPE_AGENT); }
; #define XB_SPIN(cond, bar) do { unsigned _sp = 0; while (cond) { __builtin_amdgcn_s_sleep(1); \
;     if ((++_sp & 255u) == 0u) { if (xb_ld(&(bar)[XB_TMO])) break; if (_sp > XB_SPIN_CAP) { atomicAdd(&(bar)[XB_TMO], 1u); break; } } } } while (0)
; __device__ __forceinline__ void xcd_barrier(const XcdBarrier& b) {
;     ...
;       __builtin_amdgcn_fence(__ATOMIC_RELEASE, "agent");
;       asm volatile("s_waitcnt vmcnt(0)" ::: "memory");
;       const unsigned og = xb_add(&bar[XB_TOP], 1u);
;       const unsigned tg = og / nx;
;       if (og + 1u == (tg + 1u) * nx) xb_add(&bar[XB_TOPGEN], 1u);
;       else XB_SPIN(xb_ld(&bar[XB_TOPGEN]) == tg, bar);
;       __builtin_amdgcn_fence(__ATOMIC_ACQUIRE, "agent");
;       xb_add(&bar[XB_XGEN(b.x)], 1u);
;       asm volatile("s_waitcnt vmcnt(0)" ::: "memory");
;     } else {
;       XB_SPIN(xb_ld(&bar[XB_XGEN(b.x)]) == gen, bar);
;       __builtin_amdgcn_fence(__ATOMIC_ACQUIRE, "agent");
;       asm volatile("s_waitcnt vmcnt(0)" ::: "memory");
;     }
;   }
;   __syncthreads();
; __global__ void __launch_bounds__(256, 2) fwd_megakernel(Params p) {
;     ...
;       GSYNC();
;     }
;     if (l == 0) {
;       for (int job = bid; job < 264; job += nb) norm_job(p, 1, job, false);
.LBB0_2013:
	s_or_b64 exec, exec, s[4:5]
	s_and_saveexec_b64 s[4:5], s[6:7]
	s_cbranch_execz .LBB0_2015
	global_atomic_add v[2:3], v198, off
.LBB0_2015:
	s_or_b64 exec, exec, s[4:5]
	s_waitcnt vmcnt(0) lgkmcnt(0)
	buffer_inv sc1
	s_waitcnt vmcnt(0)
.LBB0_2016:
	s_or_b64 exec, exec, s[0:1]
	v_readlane_b32 s4, v237, 29
	v_readlane_b32 s5, v237, 30
	s_mov_b64 s[0:1], -1
	s_and_b64 vcc, exec, s[4:5]
	s_waitcnt lgkmcnt(0)
	s_barrier
	s_cbranch_vccnz .LBB0_2017
	s_getpc_b64 s[98:99]
